# v5 + partial-rope cos/sin computed once per position in phase 0 (same instruction sequence) into usc/vsc scratch and loaded by the q/k norm+rope loop instead of recomputed per (token, head)
# baseline (speedup 1.0000x reference)
.LBB0_155:
	s_or_b64 exec, exec, s[0:1]
	v_subrev_u32_e32 v0, 0x19000, v134
	v_cmp_gt_u32_e32 vcc, 0x800, v0
	s_and_saveexec_b64 s[0:1], vcc
	s_cbranch_execz .Lrope_skip
	v_readlane_b32 s2, v248, 18
	v_readlane_b32 s3, v248, 19
	v_lshlrev_b32_e32 v2, 6, v0
	v_cvt_f32_u32_e32 v0, v0
	v_mul_f32_e32 v13, 0.15915494, v0
	v_rndne_f32_e32 v13, v13
	v_fmamk_f32 v15, v13, 0xc0c90fdb, v0
	v_fmac_f32_e32 v15, 0x343bbd2e, v13
	v_mul_f32_e32 v13, 0.15915494, v15
	v_cos_f32_e32 v4, v13
	v_sin_f32_e32 v16, v13
	v_mul_f32_e32 v13, 0x3e4693b0, v0
	v_mul_f32_e32 v15, 0.15915494, v13
	v_rndne_f32_e32 v15, v15
	v_fmac_f32_e32 v13, 0xc0c90fdb, v15
	v_fmac_f32_e32 v13, 0x343bbd2e, v15
	v_mul_f32_e32 v13, 0.15915494, v13
	v_cos_f32_e32 v5, v13
	v_sin_f32_e32 v17, v13
	v_mul_f32_e32 v13, 0x3d1a08c9, v0
	v_mul_f32_e32 v15, 0.15915494, v13
	v_rndne_f32_e32 v15, v15
	v_fmac_f32_e32 v13, 0xc0c90fdb, v15
	v_fmac_f32_e32 v13, 0x343bbd2e, v15
	v_mul_f32_e32 v13, 0.15915494, v13
	v_cos_f32_e32 v6, v13
	v_sin_f32_e32 v18, v13
	v_mul_f32_e32 v13, 0x3beef752, v0
	v_mul_f32_e32 v15, 0.15915494, v13
	v_rndne_f32_e32 v15, v15
	v_fmac_f32_e32 v13, 0xc0c90fdb, v15
	v_fmac_f32_e32 v13, 0x343bbd2e, v15
	v_mul_f32_e32 v13, 0.15915494, v13
	v_cos_f32_e32 v7, v13
	v_sin_f32_e32 v19, v13
	v_mul_f32_e32 v13, 0x3ab95d24, v0
	v_mul_f32_e32 v15, 0.15915494, v13
	v_rndne_f32_e32 v15, v15
	v_fmac_f32_e32 v13, 0xc0c90fdb, v15
	v_fmac_f32_e32 v13, 0x343bbd2e, v15
	v_mul_f32_e32 v13, 0.15915494, v13
	v_cos_f32_e32 v8, v13
	v_sin_f32_e32 v20, v13
	v_mul_f32_e32 v13, 0x398fc8f8, v0
	v_mul_f32_e32 v15, 0.15915494, v13
	v_rndne_f32_e32 v15, v15
	v_fmac_f32_e32 v13, 0xc0c90fdb, v15
	v_fmac_f32_e32 v13, 0x343bbd2e, v15
	v_mul_f32_e32 v13, 0.15915494, v13
	v_cos_f32_e32 v9, v13
	v_sin_f32_e32 v21, v13
	v_mul_f32_e32 v13, 0x385f10cb, v0
	v_mul_f32_e32 v15, 0.15915494, v13
	v_rndne_f32_e32 v15, v15
	v_fmac_f32_e32 v13, 0xc0c90fdb, v15
	v_fmac_f32_e32 v13, 0x343bbd2e, v15
	v_mul_f32_e32 v13, 0.15915494, v13
	v_cos_f32_e32 v10, v13
	v_sin_f32_e32 v22, v13
	v_mul_f32_e32 v13, 0x372d07a6, v0
	v_mul_f32_e32 v15, 0.15915494, v13
	v_rndne_f32_e32 v15, v15
	v_fmac_f32_e32 v13, 0xc0c90fdb, v15
	v_fmac_f32_e32 v13, 0x343bbd2e, v15
	v_mul_f32_e32 v13, 0.15915494, v13
	v_cos_f32_e32 v11, v13
	v_sin_f32_e32 v23, v13
	s_nop 1
	global_store_dwordx4 v2, v[4:7], s[2:3]
	global_store_dwordx4 v2, v[8:11], s[2:3] offset:16
	global_store_dwordx4 v2, v[16:19], s[2:3] offset:32
	global_store_dwordx4 v2, v[20:23], s[2:3] offset:48

.LBB0_411:
	s_or_b64 exec, exec, s[0:1]
	s_mov_b64 s[0:1], 0x300000
	v_cmp_gt_u64_e32 vcc, s[0:1], v[134:135]
	s_and_saveexec_b64 s[2:3], vcc
	s_cbranch_execz .LBB0_416
	v_readlane_b32 s36, v247, 45
	v_ffbh_u32_e32 v0, 0
	v_readlane_b32 s38, v247, 47
	v_readlane_b32 s39, v247, 48
	v_readlane_b32 s40, v247, 49
	v_readlane_b32 s41, v247, 50
	v_min_u32_e32 v29, 32, v0
	s_mov_b64 s[4:5], 0
	v_mov_b32_e32 v1, 0
	v_mov_b32_e32 v24, s39
	v_mov_b32_e32 v25, s41
	v_mov_b32_e32 v26, s38
	v_mov_b32_e32 v27, s40
	v_mov_b32_e32 v28, 0x358637bd
	v_sub_u32_e32 v30, 32, v29
	v_mov_b64_e32 v[2:3], v[134:135]
	v_readlane_b32 s37, v247, 46
	v_readlane_b32 s42, v248, 18
	v_readlane_b32 s43, v248, 19
	v_readlane_b32 s44, v247, 53
	v_readlane_b32 s45, v247, 54
	v_readlane_b32 s46, v247, 55
	v_readlane_b32 s47, v247, 56
	v_readlane_b32 s48, v247, 57
	v_readlane_b32 s49, v247, 58
	v_readlane_b32 s50, v247, 59
	v_readlane_b32 s51, v247, 60
	s_branch .LBB0_414

.LBB0_414:
	s_mov_b32 s0, 0xaaaaaaab
	v_mul_hi_u32 v0, v2, s0
	v_lshrrev_b32_e32 v13, 6, v0
	v_and_b32_e32 v61, 0x7ff, v13
	v_lshlrev_b32_e32 v61, 6, v61
	global_load_dwordx4 v[62:65], v61, s[42:43]
	global_load_dwordx4 v[66:69], v61, s[42:43] offset:16
	global_load_dwordx4 v[70:73], v61, s[42:43] offset:32
	global_load_dwordx4 v[74:77], v61, s[42:43] offset:48
	s_movk_i32 s0, 0x60
	v_mul_lo_u32 v0, v13, s0
	v_sub_u32_e32 v0, v2, v0
	v_ashrrev_i32_e32 v10, 2, v0
	v_mul_hi_i32_i24_e32 v5, 0x1200, v13
	v_mul_i32_i24_e32 v4, 0x1200, v13
	v_lshlrev_b32_e32 v6, 6, v10
	v_and_b32_e32 v31, 3, v0
	v_lshl_add_u64 v[4:5], s[70:71], 0, v[4:5]
	v_ashrrev_i32_e32 v7, 31, v6
	v_lshl_add_u64 v[4:5], v[6:7], 1, v[4:5]
	v_lshlrev_b32_e32 v0, 5, v31
	v_lshl_add_u64 v[4:5], v[4:5], 0, v[0:1]
	global_load_dwordx4 v[6:9], v[4:5], off
	global_load_dwordx4 v[14:17], v[4:5], off offset:16
	v_lshlrev_b32_e32 v0, 4, v10
	v_cmp_lt_i32_e32 vcc, 11, v10
	v_add_u32_e32 v12, 0xffffff40, v0
	s_mov_b32 s0, 0x800000
	v_cndmask_b32_e32 v0, v0, v12, vcc
	v_and_b32_e32 v18, 0xffffffc0, v0
	v_cndmask_b32_e32 v11, v24, v25, vcc
	v_cndmask_b32_e32 v10, v26, v27, vcc
	v_ashrrev_i32_e32 v19, 31, v18
	v_lshlrev_b32_e32 v0, 6, v31
	v_lshl_add_u64 v[10:11], v[18:19], 2, v[10:11]
	v_lshl_add_u64 v[10:11], v[10:11], 0, v[0:1]
	global_load_dwordx4 v[18:21], v[10:11], off
	global_load_dwordx4 v[32:35], v[10:11], off offset:16
	global_load_dwordx4 v[36:39], v[10:11], off offset:32
	global_load_dwordx4 v[40:43], v[10:11], off offset:48
	s_waitcnt vmcnt(5)
	v_lshlrev_b32_e32 v10, 16, v6
	v_and_b32_e32 v11, 0xffff0000, v6
	v_lshlrev_b32_e32 v6, 16, v7
	v_and_b32_e32 v7, 0xffff0000, v7
	v_pk_mul_f32 v[48:49], v[10:11], v[10:11]
	v_pk_mul_f32 v[52:53], v[6:7], v[6:7]
	v_add_f32_e32 v0, v48, v49
	v_lshlrev_b32_e32 v22, 16, v8
	v_and_b32_e32 v23, 0xffff0000, v8
	v_add_f32_e32 v0, v0, v52
	v_pk_mul_f32 v[56:57], v[22:23], v[22:23]
	v_add_f32_e32 v0, v53, v0
	v_add_f32_e32 v0, v56, v0
	v_lshlrev_b32_e32 v12, 16, v9
	v_add_f32_e32 v0, v57, v0
	v_and_b32_e32 v60, 0xffff0000, v9
	s_waitcnt vmcnt(4)
	v_lshlrev_b32_e32 v8, 16, v14
	v_and_b32_e32 v9, 0xffff0000, v14
	v_fmac_f32_e32 v0, v12, v12
	v_pk_mul_f32 v[50:51], v[8:9], v[8:9]
	v_fmac_f32_e32 v0, v60, v60
	v_lshlrev_b32_e32 v14, 16, v15
	v_and_b32_e32 v15, 0xffff0000, v15
	v_add_f32_e32 v0, v50, v0
	v_pk_mul_f32 v[54:55], v[14:15], v[14:15]
	v_add_f32_e32 v0, v51, v0
	v_lshlrev_b32_e32 v44, 16, v16
	v_and_b32_e32 v45, 0xffff0000, v16
	v_add_f32_e32 v0, v54, v0
	v_pk_mul_f32 v[58:59], v[44:45], v[44:45]
	v_add_f32_e32 v0, v55, v0
	v_lshlrev_b32_e32 v47, 16, v17
	v_and_b32_e32 v46, 0xffff0000, v17
	v_add_f32_e32 v0, v58, v0
	v_pk_mul_f32 v[16:17], v[46:47], v[46:47]
	v_add_f32_e32 v0, v59, v0
	v_add_f32_e32 v0, v17, v0
	v_add_f32_e32 v0, v16, v0
	s_nop 1
	v_add_f32_dpp v0, v0, v0 quad_perm:[1,0,3,2] row_mask:0xf bank_mask:0xf bound_ctrl:1
	s_nop 1
	v_add_f32_dpp v0, v0, v0 quad_perm:[2,3,0,1] row_mask:0xf bank_mask:0xf bound_ctrl:1
	v_fmamk_f32 v0, v0, 0x3c800000, v28
	v_mul_f32_e32 v16, 0x4b800000, v0
	v_cmp_gt_f32_e64 s[0:1], s0, v0
	s_nop 1
	v_cndmask_b32_e64 v0, v0, v16, s[0:1]
	v_rsq_f32_e32 v0, v0
	s_nop 0
	v_mul_f32_e32 v16, 0x45800000, v0
	v_cndmask_b32_e64 v0, v0, v16, s[0:1]
	v_mul_f32_e32 v16, 0x3e000000, v0
	v_cndmask_b32_e32 v0, v16, v0, vcc
	v_pk_mul_f32 v[10:11], v[0:1], v[10:11] op_sel_hi:[0,1]
	v_pk_mul_f32 v[16:17], v[0:1], v[22:23] op_sel_hi:[0,1]
	v_mul_f32_e32 v12, v0, v12
	v_mul_f32_e32 v48, v0, v47
	v_mov_b32_e32 v47, v60
	v_pk_mul_f32 v[6:7], v[0:1], v[6:7] op_sel_hi:[0,1]
	v_pk_mul_f32 v[8:9], v[0:1], v[8:9] op_sel_hi:[0,1]
	v_pk_mul_f32 v[14:15], v[0:1], v[14:15] op_sel_hi:[0,1]
	v_pk_mul_f32 v[44:45], v[0:1], v[44:45] op_sel_hi:[0,1]
	s_waitcnt vmcnt(3)
	v_pk_mul_f32 v[22:23], v[18:19], v[10:11]
	s_waitcnt vmcnt(2)
	v_pk_mul_f32 v[18:19], v[32:33], v[16:17]
	v_mul_f32_e32 v12, v34, v12
	v_pk_mul_f32 v[16:17], v[0:1], v[46:47] op_sel_hi:[0,1]
	s_waitcnt vmcnt(0)
	v_mov_b32_e32 v34, v43
	v_pk_mul_f32 v[20:21], v[20:21], v[6:7]
	v_pk_mul_f32 v[6:7], v[36:37], v[8:9]
	v_pk_mul_f32 v[8:9], v[38:39], v[14:15]
	v_pk_mul_f32 v[10:11], v[40:41], v[44:45]
	v_mul_f32_e32 v14, v42, v48
	v_pk_mul_f32 v[16:17], v[34:35], v[16:17]
	v_cmp_eq_u32_e32 vcc, 0, v31
	s_and_saveexec_b64 s[0:1], vcc
	s_cbranch_execz .LBB0_413
	v_pk_mul_f32 v[36:37], v[70:71], v[6:7]
	v_pk_fma_f32 v[36:37], v[62:63], v[22:23], v[36:37] neg_lo:[0,0,1] neg_hi:[0,0,1]
	v_pk_mul_f32 v[22:23], v[70:71], v[22:23]
	v_pk_mul_f32 v[34:35], v[72:73], v[8:9]
	v_pk_fma_f32 v[6:7], v[62:63], v[6:7], v[22:23]
	v_pk_fma_f32 v[34:35], v[64:65], v[20:21], v[34:35] neg_lo:[0,0,1] neg_hi:[0,0,1]
	v_pk_mul_f32 v[20:21], v[72:73], v[20:21]
	v_pk_mul_f32 v[32:33], v[74:75], v[10:11]
	v_pk_fma_f32 v[8:9], v[64:65], v[8:9], v[20:21]
	v_pk_fma_f32 v[32:33], v[66:67], v[18:19], v[32:33] neg_lo:[0,0,1] neg_hi:[0,0,1]
	v_pk_mul_f32 v[18:19], v[74:75], v[18:19]
	v_mov_b32_e32 v15, v16
	v_pk_fma_f32 v[10:11], v[66:67], v[10:11], v[18:19]
	v_mul_f32_e32 v22, v68, v14
	v_mul_f32_e32 v38, v76, v12
	v_mov_b32_e32 v13, v17
	v_mov_b32_e32 v78, v69
	v_mov_b32_e32 v79, v77
	v_pk_mul_f32 v[14:15], v[76:77], v[14:15]
	s_nop 0
	v_pk_fma_f32 v[12:13], v[68:69], v[12:13], v[14:15] neg_lo:[0,0,1] neg_hi:[0,0,1]
	v_pk_mul_f32 v[14:15], v[78:79], v[16:17]
	v_mov_b32_e32 v20, v34
	v_mov_b32_e32 v23, v14
	v_mov_b32_e32 v39, v15
	s_nop 0
	v_pk_add_f32 v[14:15], v[22:23], v[38:39]
	v_mov_b32_e32 v22, v36
	v_mov_b32_e32 v23, v37
	v_mov_b32_e32 v21, v35
	v_mov_b32_e32 v18, v32
	v_mov_b32_e32 v19, v33
	v_mov_b32_e32 v17, v13
	v_mov_b32_e32 v16, v15
	s_branch .LBB0_413
